# attention: remove dead per-tile save/restore movs of next-item Q/bias registers (plus V-read hoist, LDS double buffer, far-tile fast path, relu2 epilogue, scan sa)
# speedup vs baseline: 1.0024x; 1.0005x over previous
; #define ATT_LOAD(I_, tile) do { _Pragma("unroll") for (int p_ = 0; p_ < 2; ++p_) { \
;         kreg[p_] = *(const u32x4*)((I_).Kb + (size_t)((tile) * 64 + kr + 32 * p_) * (I_).ldk + kc * 8); \
;         vreg[p_] = *(const u32x4*)((I_).Vb + (size_t)(vr + 64 * p_) * (I_).ldv + (tile) * 64 + vc * 8); } } while (0)
; #define ATT_LOADQ(dst_, I_) do { _Pragma("unroll") for (int ks = 0; ks < 4; ++ks) dst_[ks] = *(const bf16x8*)(qk + (size_t)(I_).qrow * 4096 + (I_).h * 128 + 32 * ks + 8 * g); } while (0)
; __device__ __forceinline__ void phase_attn(const DArgs& a, LAS unsigned char* lds) {
;     ...
;             if (tile < cur.tile_hi) ATT_LOAD(cur, tile + 1);
;             else if (has_next) { ATT_LOAD(nxt, nxt.tile_lo); ATT_LOADQ(qfn, nxt); biasn = tid < 257 ? relb[nxt.h * 257 + tid] : 0.f; }
.LBB0_1389:
	s_add_i32 s0, s16, 64
	s_waitcnt vmcnt(5)
	v_add_u32_e32 v12, s16, v105
	s_waitcnt vmcnt(4)
	v_add_u32_e32 v2, 64, v12
	s_ashr_i32 s1, s0, 31
	v_lshl_add_u64 v[0:1], s[0:1], 1, v[118:119]
	v_ashrrev_i32_e32 v5, 31, v2
	v_mad_u64_u32 v[2:3], s[0:1], v2, s59, 0
	v_mov_b32_e32 v4, v3
	v_mad_u64_u32 v[4:5], s[0:1], v5, s59, v[4:5]
	v_mov_b32_e32 v3, v4
	v_lshl_add_u64 v[2:3], v[2:3], 1, v[116:117]
	global_load_dwordx4 v[8:11], v[2:3], off
	v_lshl_add_u64 v[2:3], v[128:129], 1, v[0:1]
	global_load_dwordx4 v[4:7], v[2:3], off
	v_add_u32_e32 v2, 0x60, v12
	v_ashrrev_i32_e32 v13, 31, v2
	v_mad_u64_u32 v[2:3], s[0:1], v2, s59, 0
	v_mov_b32_e32 v12, v3
	v_mad_u64_u32 v[12:13], s[0:1], v13, s59, v[12:13]
	v_mov_b32_e32 v3, v12
	v_lshl_add_u64 v[2:3], v[2:3], 1, v[116:117]
	v_lshl_add_u64 v[0:1], v[130:131], 1, v[0:1]
	global_load_dwordx4 v[12:15], v[2:3], off
	s_waitcnt vmcnt(3)
	s_nop 0
	global_load_dwordx4 v[0:3], v[0:1], off
	s_nop 0
	s_nop 0
	s_nop 0
	s_nop 0
	s_nop 0
	s_nop 0
	s_nop 0
	s_nop 0
	s_and_saveexec_b64 s[44:45], s[22:23]
	s_cbranch_execnz .LBB0_1383

; #define ATT_LOAD(I_, tile) do { _Pragma("unroll") for (int p_ = 0; p_ < 2; ++p_) { \
;         kreg[p_] = *(const u32x4*)((I_).Kb + (size_t)((tile) * 64 + kr + 32 * p_) * (I_).ldk + kc * 8); \
;         vreg[p_] = *(const u32x4*)((I_).Vb + (size_t)(vr + 64 * p_) * (I_).ldv + (tile) * 64 + vc * 8); } } while (0)
; #define ATT_LOADQ(dst_, I_) do { _Pragma("unroll") for (int ks = 0; ks < 4; ++ks) dst_[ks] = *(const bf16x8*)(qk + (size_t)(I_).qrow * 4096 + (I_).h * 128 + 32 * ks + 8 * g); } while (0)
; __device__ __forceinline__ void phase_attn(const DArgs& a, LAS unsigned char* lds) {
;     ...
;         for (int tile = cur.tile_lo; tile <= cur.tile_hi; ++tile) {
;             if (tile < cur.tile_hi) ATT_LOAD(cur, tile + 1);
;             else if (has_next) { ATT_LOAD(nxt, nxt.tile_lo); ATT_LOADQ(qfn, nxt); biasn = tid < 257 ? relb[nxt.h * 257 + tid] : 0.f; }
;             const bool act = cur.wact && (!cur.prompt || (tile >= cur.qc - 8 && tile <= cur.qc));
.LBB0_1392:
	s_add_i32 s63, s63, 1
	s_add_i32 s16, s16, 64
	v_subrev_u32_e32 v111, 64, v111
	s_and_b64 vcc, exec, s[40:41]
	s_cbranch_vccnz .LBB0_1395
	s_waitcnt vmcnt(0)
	s_nop 0
	s_nop 0
	s_nop 0
	s_nop 0
	s_nop 0
	s_nop 0
	s_nop 0
	s_nop 0
	s_nop 0
	s_branch .LBB0_1376
